# spatial gating MFMA section: redundant full LDS wait after the first transposed-read group removed (the following counted wait already covers it)
# baseline (speedup 1.0000x reference)
.LBB0_704:
	s_waitcnt lgkmcnt(0)
	s_barrier
	ds_read_b64_tr_b16 v[36:37], v161
	ds_read_b64_tr_b16 v[38:39], v161 offset:2304
	ds_read_b64_tr_b16 v[32:33], v161 offset:8
	ds_read_b64_tr_b16 v[34:35], v161 offset:2312
	ds_read_b128 v[40:43], v177
	ds_read_b128 v[48:51], v177 offset:13056
	s_waitcnt lgkmcnt(1)
	v_mfma_f32_16x16x32_bf16 v[92:95], v[36:39], v[40:43], 0
	ds_read_b128 v[56:59], v177 offset:17408
	ds_read_b128 v[64:67], v177 offset:21760
	s_lshl_b32 s5, s44, 7
	v_mfma_f32_16x16x32_bf16 v[88:91], v[32:35], v[40:43], 0
	ds_read_b128 v[40:43], v177 offset:4352
	v_or_b32_e32 v144, s5, v183
	v_lshlrev_b32_e32 v144, 2, v144
	global_load_dword v196, v144, s[16:17]
	v_or_b32_e32 v212, s5, v182
	v_lshlrev_b32_e32 v212, 2, v212
	global_load_dword v198, v212, s[16:17]
	v_or_b32_e32 v212, s5, v181
	v_lshlrev_b32_e32 v212, 2, v212
	global_load_dword v200, v212, s[16:17]
	v_or_b32_e32 v212, s5, v180
	v_lshlrev_b32_e32 v212, 2, v212
	global_load_dword v202, v212, s[16:17]
	v_or_b32_e32 v212, s5, v179
	v_lshlrev_b32_e32 v212, 2, v212
	global_load_dword v204, v212, s[16:17]
	v_or_b32_e32 v212, s5, v178
	v_lshlrev_b32_e32 v212, 2, v212
	global_load_dword v206, v212, s[16:17]
	v_or_b32_e32 v212, s5, v113
	v_lshlrev_b32_e32 v212, 2, v212
	global_load_dword v208, v212, s[16:17]
	v_or_b32_e32 v212, s5, v111
	v_lshlrev_b32_e32 v212, 2, v212
	global_load_dword v210, v212, s[16:17]
	s_waitcnt lgkmcnt(0)
	v_mfma_f32_16x16x32_bf16 v[84:87], v[36:39], v[40:43], 0
	s_lshl_b32 s30, s4, 1
	v_lshl_add_u64 v[116:117], v[98:99], 0, s[30:31]
	s_add_i32 s27, s27, s74
	v_mfma_f32_16x16x32_bf16 v[80:83], v[32:35], v[40:43], 0
	ds_read_b128 v[40:43], v177 offset:8704
	s_cmpk_gt_i32 s27, 0x43f
	v_mfma_f32_16x16x32_bf16 v[146:149], v[36:39], v[64:67], 0
	v_mfma_f32_16x16x32_bf16 v[150:153], v[32:35], v[64:67], 0
	ds_read_b128 v[64:67], v177 offset:26112
	s_waitcnt lgkmcnt(0)
	v_mfma_f32_16x16x32_bf16 v[154:157], v[36:39], v[64:67], 0
	v_mfma_f32_16x16x32_bf16 v[184:187], v[32:35], v[64:67], 0
	ds_read_b128 v[64:67], v177 offset:30464
	ds_read_b64_tr_b16 v[192:193], v162
	ds_read_b64_tr_b16 v[194:195], v162 offset:2304
	ds_read_b64_tr_b16 v[188:189], v162 offset:8
	ds_read_b64_tr_b16 v[190:191], v162 offset:2312
	s_waitcnt lgkmcnt(0)
	v_mfma_f32_16x16x32_bf16 v[44:47], v[36:39], v[40:43], 0
	v_mfma_f32_16x16x32_bf16 v[40:43], v[32:35], v[40:43], 0
	v_mfma_f32_16x16x32_bf16 v[52:55], v[36:39], v[48:51], 0
	v_mfma_f32_16x16x32_bf16 v[48:51], v[32:35], v[48:51], 0
	v_mfma_f32_16x16x32_bf16 v[60:63], v[36:39], v[56:59], 0
	v_mfma_f32_16x16x32_bf16 v[56:59], v[32:35], v[56:59], 0
	s_waitcnt lgkmcnt(0)
	v_mfma_f32_16x16x32_bf16 v[36:39], v[36:39], v[64:67], 0
	v_mfma_f32_16x16x32_bf16 v[32:35], v[32:35], v[64:67], 0
	ds_read_b128 v[64:67], v177 offset:8768
	s_waitcnt lgkmcnt(0)
	v_mfma_f32_16x16x32_bf16 v[72:75], v[188:191], v[64:67], v[40:43]
	s_nop 2
	ds_read_b128 v[40:43], v177 offset:13120
	v_mfma_f32_16x16x32_bf16 v[76:79], v[192:195], v[64:67], v[44:47]
	s_waitcnt lgkmcnt(0)
	v_mfma_f32_16x16x32_bf16 v[68:71], v[192:195], v[40:43], v[52:55]
	v_mfma_f32_16x16x32_bf16 v[64:67], v[188:191], v[40:43], v[48:51]
	ds_read_b128 v[40:43], v177 offset:17472
	s_nop 1
	ds_read_b128 v[48:51], v177 offset:21824
	s_waitcnt lgkmcnt(1)
	v_mfma_f32_16x16x32_bf16 v[44:47], v[192:195], v[40:43], v[60:63]
	v_mfma_f32_16x16x32_bf16 v[40:43], v[188:191], v[40:43], v[56:59]
	s_nop 2
	ds_read_b128 v[56:59], v177 offset:26176
	s_waitcnt lgkmcnt(1)
	v_mfma_f32_16x16x32_bf16 v[52:55], v[192:195], v[48:51], v[146:149]
	v_mfma_f32_16x16x32_bf16 v[48:51], v[188:191], v[48:51], v[150:153]
	s_waitcnt lgkmcnt(0)
	v_mfma_f32_16x16x32_bf16 v[146:149], v[192:195], v[56:59], v[154:157]
	v_mfma_f32_16x16x32_bf16 v[150:153], v[188:191], v[56:59], v[184:187]
	ds_read_b128 v[56:59], v177 offset:30528
	ds_read_b64_tr_b16 v[184:185], v163
	ds_read_b64_tr_b16 v[186:187], v163 offset:2304
	ds_read_b64_tr_b16 v[154:155], v163 offset:8
	ds_read_b64_tr_b16 v[156:157], v163 offset:2312
	s_waitcnt lgkmcnt(0)
	s_waitcnt lgkmcnt(0)
	v_mfma_f32_16x16x32_bf16 v[36:39], v[192:195], v[56:59], v[36:39]
	v_mfma_f32_16x16x32_bf16 v[32:35], v[188:191], v[56:59], v[32:35]
	ds_read_b128 v[56:59], v177 offset:17536
	s_waitcnt lgkmcnt(0)
	v_mfma_f32_16x16x32_bf16 v[60:63], v[184:187], v[56:59], v[44:47]
	v_mfma_f32_16x16x32_bf16 v[56:59], v[154:157], v[56:59], v[40:43]
	s_nop 2
	ds_read_b128 v[40:43], v177 offset:21888
	s_waitcnt lgkmcnt(0)
	v_mfma_f32_16x16x32_bf16 v[52:55], v[184:187], v[40:43], v[52:55]
	v_mfma_f32_16x16x32_bf16 v[48:51], v[154:157], v[40:43], v[48:51]
	ds_read_b128 v[40:43], v177 offset:26240
	s_waitcnt lgkmcnt(0)
	v_mfma_f32_16x16x32_bf16 v[44:47], v[184:187], v[40:43], v[146:149]
	s_nop 2
	ds_read_b128 v[146:149], v177 offset:30592
	v_mfma_f32_16x16x32_bf16 v[40:43], v[154:157], v[40:43], v[150:153]
	s_waitcnt lgkmcnt(0)
	v_mfma_f32_16x16x32_bf16 v[36:39], v[184:187], v[146:149], v[36:39]
	v_mfma_f32_16x16x32_bf16 v[32:35], v[154:157], v[146:149], v[32:35]
	ds_read_b64_tr_b16 v[150:151], v164
	ds_read_b64_tr_b16 v[152:153], v164 offset:2304
	ds_read_b64_tr_b16 v[146:147], v164 offset:8
	ds_read_b64_tr_b16 v[148:149], v164 offset:2312
	s_waitcnt lgkmcnt(0)
	ds_read_b128 v[154:157], v177 offset:26304
	s_waitcnt lgkmcnt(0)
	v_mfma_f32_16x16x32_bf16 v[44:47], v[150:153], v[154:157], v[44:47]
	s_waitcnt vmcnt(0)
	v_pk_add_f32 v[92:93], v[92:93], v[196:197] op_sel_hi:[1,0]
	v_mfma_f32_16x16x32_bf16 v[40:43], v[146:149], v[154:157], v[40:43]
	ds_read_b128 v[154:157], v177 offset:30656
	v_pk_add_f32 v[94:95], v[94:95], v[196:197] op_sel_hi:[1,0]
	v_pk_add_f32 v[88:89], v[88:89], v[196:197] op_sel_hi:[1,0]
	s_waitcnt lgkmcnt(0)
	v_mfma_f32_16x16x32_bf16 v[32:35], v[146:149], v[154:157], v[32:35]
	v_lshlrev_b32_e32 v146, 16, v28
	v_and_b32_e32 v147, 0xffff0000, v28
	v_pk_mul_f32 v[92:93], v[92:93], v[146:147]
	v_pk_add_f32 v[90:91], v[90:91], v[196:197] op_sel_hi:[1,0]
	v_cvt_pk_bf16_f32 v28, v92, v93
	v_lshlrev_b32_e32 v92, 16, v29
	v_and_b32_e32 v93, 0xffff0000, v29
	v_pk_mul_f32 v[92:93], v[94:95], v[92:93]
	v_mfma_f32_16x16x32_bf16 v[36:39], v[150:153], v[154:157], v[36:39]
	v_cvt_pk_bf16_f32 v29, v92, v93
	v_lshlrev_b32_e32 v92, 16, v30
	v_and_b32_e32 v93, 0xffff0000, v30
	v_pk_mul_f32 v[88:89], v[88:89], v[92:93]
	s_nop 0
	v_cvt_pk_bf16_f32 v30, v88, v89
	v_lshlrev_b32_e32 v88, 16, v31
	v_and_b32_e32 v89, 0xffff0000, v31
	v_pk_mul_f32 v[88:89], v[90:91], v[88:89]
	s_nop 0
	v_cvt_pk_bf16_f32 v31, v88, v89
	v_lshlrev_b64 v[88:89], 12, v[114:115]
	v_lshl_add_u64 v[88:89], v[116:117], 0, v[88:89]
	global_store_dwordx4 v[88:89], v[28:31], off
	v_lshlrev_b32_e32 v88, 16, v24
	v_and_b32_e32 v89, 0xffff0000, v24
	v_or_b32_e32 v29, s5, v182
	v_lshlrev_b32_e32 v29, 2, v29
	v_or_b32_e32 v28, s43, v122
	v_ashrrev_i32_e32 v29, 31, v28
	v_lshlrev_b64 v[28:29], 12, v[28:29]
	v_lshl_add_u64 v[28:29], v[116:117], 0, v[28:29]
	v_pk_add_f32 v[84:85], v[84:85], v[198:199] op_sel_hi:[1,0]
	s_nop 0
	v_pk_mul_f32 v[84:85], v[84:85], v[88:89]
	v_pk_add_f32 v[86:87], v[86:87], v[198:199] op_sel_hi:[1,0]
	v_cvt_pk_bf16_f32 v24, v84, v85
	v_lshlrev_b32_e32 v84, 16, v25
	v_and_b32_e32 v85, 0xffff0000, v25
	v_pk_mul_f32 v[84:85], v[86:87], v[84:85]
	v_pk_add_f32 v[80:81], v[80:81], v[198:199] op_sel_hi:[1,0]
	v_cvt_pk_bf16_f32 v25, v84, v85
	v_lshlrev_b32_e32 v84, 16, v26
	v_and_b32_e32 v85, 0xffff0000, v26
	v_pk_mul_f32 v[80:81], v[80:81], v[84:85]
	v_pk_add_f32 v[30:31], v[82:83], v[198:199] op_sel_hi:[1,0]
	v_cvt_pk_bf16_f32 v26, v80, v81
	v_lshlrev_b32_e32 v80, 16, v27
	v_and_b32_e32 v81, 0xffff0000, v27
	v_pk_mul_f32 v[30:31], v[30:31], v[80:81]
	s_nop 0
	v_cvt_pk_bf16_f32 v27, v30, v31
	global_store_dwordx4 v[28:29], v[24:27], off
	v_lshlrev_b32_e32 v28, 16, v20
	v_and_b32_e32 v29, 0xffff0000, v20
	v_or_b32_e32 v25, s5, v181
	v_lshlrev_b32_e32 v25, 2, v25
	v_or_b32_e32 v24, s43, v123
	v_ashrrev_i32_e32 v25, 31, v24
	v_lshlrev_b64 v[24:25], 12, v[24:25]
	v_lshl_add_u64 v[24:25], v[116:117], 0, v[24:25]
	v_pk_add_f32 v[30:31], v[76:77], v[200:201] op_sel_hi:[1,0]
	s_nop 0
	v_pk_mul_f32 v[28:29], v[30:31], v[28:29]
	v_pk_add_f32 v[30:31], v[78:79], v[200:201] op_sel_hi:[1,0]
	v_cvt_pk_bf16_f32 v20, v28, v29
	v_lshlrev_b32_e32 v28, 16, v21
	v_and_b32_e32 v29, 0xffff0000, v21
	v_pk_mul_f32 v[28:29], v[30:31], v[28:29]
	v_pk_add_f32 v[30:31], v[72:73], v[200:201] op_sel_hi:[1,0]
	v_cvt_pk_bf16_f32 v21, v28, v29
	v_lshlrev_b32_e32 v28, 16, v22
	v_and_b32_e32 v29, 0xffff0000, v22
	v_pk_mul_f32 v[28:29], v[30:31], v[28:29]
	v_pk_add_f32 v[26:27], v[74:75], v[200:201] op_sel_hi:[1,0]
	v_cvt_pk_bf16_f32 v22, v28, v29
	v_lshlrev_b32_e32 v28, 16, v23
	v_and_b32_e32 v29, 0xffff0000, v23
	v_pk_mul_f32 v[26:27], v[26:27], v[28:29]
	s_nop 0
	v_cvt_pk_bf16_f32 v23, v26, v27
	global_store_dwordx4 v[24:25], v[20:23], off
	v_lshlrev_b32_e32 v24, 16, v16
	v_and_b32_e32 v25, 0xffff0000, v16
	v_or_b32_e32 v21, s5, v180
	v_lshlrev_b32_e32 v21, 2, v21
	v_or_b32_e32 v20, s43, v124
	v_ashrrev_i32_e32 v21, 31, v20
	v_lshlrev_b64 v[20:21], 12, v[20:21]
	v_lshl_add_u64 v[20:21], v[116:117], 0, v[20:21]
	v_pk_add_f32 v[26:27], v[68:69], v[202:203] op_sel_hi:[1,0]
	s_nop 0
	v_pk_mul_f32 v[24:25], v[26:27], v[24:25]
	v_pk_add_f32 v[26:27], v[70:71], v[202:203] op_sel_hi:[1,0]
	v_cvt_pk_bf16_f32 v16, v24, v25
	v_lshlrev_b32_e32 v24, 16, v17
	v_and_b32_e32 v25, 0xffff0000, v17
	v_pk_mul_f32 v[24:25], v[26:27], v[24:25]
	v_pk_add_f32 v[26:27], v[64:65], v[202:203] op_sel_hi:[1,0]
	v_cvt_pk_bf16_f32 v17, v24, v25
	v_lshlrev_b32_e32 v24, 16, v18
	v_and_b32_e32 v25, 0xffff0000, v18
	v_pk_mul_f32 v[24:25], v[26:27], v[24:25]
	v_pk_add_f32 v[22:23], v[66:67], v[202:203] op_sel_hi:[1,0]
	v_cvt_pk_bf16_f32 v18, v24, v25
	v_lshlrev_b32_e32 v24, 16, v19
	v_and_b32_e32 v25, 0xffff0000, v19
	v_pk_mul_f32 v[22:23], v[22:23], v[24:25]
	s_nop 0
	v_cvt_pk_bf16_f32 v19, v22, v23
	global_store_dwordx4 v[20:21], v[16:19], off
	v_lshlrev_b32_e32 v20, 16, v12
	v_and_b32_e32 v21, 0xffff0000, v12
	v_or_b32_e32 v17, s5, v179
	v_lshlrev_b32_e32 v17, 2, v17
	v_or_b32_e32 v16, s43, v125
	v_ashrrev_i32_e32 v17, 31, v16
	v_lshlrev_b64 v[16:17], 12, v[16:17]
	v_lshl_add_u64 v[16:17], v[116:117], 0, v[16:17]
	v_pk_add_f32 v[22:23], v[60:61], v[204:205] op_sel_hi:[1,0]
	s_nop 0
	v_pk_mul_f32 v[20:21], v[22:23], v[20:21]
	v_pk_add_f32 v[22:23], v[62:63], v[204:205] op_sel_hi:[1,0]
	v_cvt_pk_bf16_f32 v12, v20, v21
	v_lshlrev_b32_e32 v20, 16, v13
	v_and_b32_e32 v21, 0xffff0000, v13
	v_pk_mul_f32 v[20:21], v[22:23], v[20:21]
	v_pk_add_f32 v[22:23], v[56:57], v[204:205] op_sel_hi:[1,0]
	v_cvt_pk_bf16_f32 v13, v20, v21
	v_lshlrev_b32_e32 v20, 16, v14
	v_and_b32_e32 v21, 0xffff0000, v14
	v_pk_mul_f32 v[20:21], v[22:23], v[20:21]
	v_pk_add_f32 v[18:19], v[58:59], v[204:205] op_sel_hi:[1,0]
	v_cvt_pk_bf16_f32 v14, v20, v21
	v_lshlrev_b32_e32 v20, 16, v15
	v_and_b32_e32 v21, 0xffff0000, v15
	v_pk_mul_f32 v[18:19], v[18:19], v[20:21]
	s_nop 0
	v_cvt_pk_bf16_f32 v15, v18, v19
	global_store_dwordx4 v[16:17], v[12:15], off
	v_lshlrev_b32_e32 v16, 16, v8
	v_and_b32_e32 v17, 0xffff0000, v8
	v_or_b32_e32 v13, s5, v178
	v_lshlrev_b32_e32 v13, 2, v13
	v_or_b32_e32 v12, s43, v126
	v_ashrrev_i32_e32 v13, 31, v12
	v_lshlrev_b64 v[12:13], 12, v[12:13]
	v_lshl_add_u64 v[12:13], v[116:117], 0, v[12:13]
	v_pk_add_f32 v[18:19], v[52:53], v[206:207] op_sel_hi:[1,0]
	s_nop 0
	v_pk_mul_f32 v[16:17], v[18:19], v[16:17]
	v_pk_add_f32 v[18:19], v[54:55], v[206:207] op_sel_hi:[1,0]
	v_cvt_pk_bf16_f32 v8, v16, v17
	v_lshlrev_b32_e32 v16, 16, v9
	v_and_b32_e32 v17, 0xffff0000, v9
	v_pk_mul_f32 v[16:17], v[18:19], v[16:17]
	v_pk_add_f32 v[18:19], v[48:49], v[206:207] op_sel_hi:[1,0]
	v_cvt_pk_bf16_f32 v9, v16, v17
	v_lshlrev_b32_e32 v16, 16, v10
	v_and_b32_e32 v17, 0xffff0000, v10
	v_pk_mul_f32 v[16:17], v[18:19], v[16:17]
	v_pk_add_f32 v[14:15], v[50:51], v[206:207] op_sel_hi:[1,0]
	v_cvt_pk_bf16_f32 v10, v16, v17
	v_lshlrev_b32_e32 v16, 16, v11
	v_and_b32_e32 v17, 0xffff0000, v11
	v_pk_mul_f32 v[14:15], v[14:15], v[16:17]
	s_nop 0
	v_cvt_pk_bf16_f32 v11, v14, v15
	global_store_dwordx4 v[12:13], v[8:11], off
	v_lshlrev_b32_e32 v12, 16, v4
	v_and_b32_e32 v13, 0xffff0000, v4
	v_or_b32_e32 v9, s5, v113
	v_lshlrev_b32_e32 v9, 2, v9
	v_or_b32_e32 v8, s43, v127
	v_ashrrev_i32_e32 v9, 31, v8
	v_lshlrev_b64 v[8:9], 12, v[8:9]
	v_lshl_add_u64 v[8:9], v[116:117], 0, v[8:9]
	v_pk_add_f32 v[14:15], v[44:45], v[208:209] op_sel_hi:[1,0]
	s_nop 0
	v_pk_mul_f32 v[12:13], v[14:15], v[12:13]
	v_pk_add_f32 v[14:15], v[46:47], v[208:209] op_sel_hi:[1,0]
	v_cvt_pk_bf16_f32 v4, v12, v13
	v_lshlrev_b32_e32 v12, 16, v5
	v_and_b32_e32 v13, 0xffff0000, v5
	v_pk_mul_f32 v[12:13], v[14:15], v[12:13]
	v_pk_add_f32 v[14:15], v[40:41], v[208:209] op_sel_hi:[1,0]
	v_cvt_pk_bf16_f32 v5, v12, v13
	v_lshlrev_b32_e32 v12, 16, v6
	v_and_b32_e32 v13, 0xffff0000, v6
	v_pk_mul_f32 v[12:13], v[14:15], v[12:13]
	v_pk_add_f32 v[10:11], v[42:43], v[208:209] op_sel_hi:[1,0]
	v_cvt_pk_bf16_f32 v6, v12, v13
	v_lshlrev_b32_e32 v12, 16, v7
	v_and_b32_e32 v13, 0xffff0000, v7
	v_pk_mul_f32 v[10:11], v[10:11], v[12:13]
	s_nop 0
	v_cvt_pk_bf16_f32 v7, v10, v11
	global_store_dwordx4 v[8:9], v[4:7], off
	v_lshlrev_b32_e32 v8, 16, v0
	v_and_b32_e32 v9, 0xffff0000, v0
	v_or_b32_e32 v5, s5, v111
	v_lshlrev_b32_e32 v5, 2, v5
	v_or_b32_e32 v4, s43, v121
	v_ashrrev_i32_e32 v5, 31, v4
	v_lshlrev_b64 v[4:5], 12, v[4:5]
	v_lshl_add_u64 v[4:5], v[116:117], 0, v[4:5]
	v_pk_add_f32 v[10:11], v[36:37], v[210:211] op_sel_hi:[1,0]
	s_nop 0
	v_pk_mul_f32 v[8:9], v[10:11], v[8:9]
	v_pk_add_f32 v[10:11], v[38:39], v[210:211] op_sel_hi:[1,0]
	v_cvt_pk_bf16_f32 v0, v8, v9
	v_lshlrev_b32_e32 v8, 16, v1
	v_and_b32_e32 v9, 0xffff0000, v1
	v_pk_mul_f32 v[8:9], v[10:11], v[8:9]
	v_pk_add_f32 v[10:11], v[32:33], v[210:211] op_sel_hi:[1,0]
	v_cvt_pk_bf16_f32 v1, v8, v9
	v_lshlrev_b32_e32 v8, 16, v2
	v_and_b32_e32 v9, 0xffff0000, v2
	v_pk_mul_f32 v[8:9], v[10:11], v[8:9]
	v_pk_add_f32 v[6:7], v[34:35], v[210:211] op_sel_hi:[1,0]
	v_cvt_pk_bf16_f32 v2, v8, v9
	v_lshlrev_b32_e32 v8, 16, v3
	v_and_b32_e32 v9, 0xffff0000, v3
	v_pk_mul_f32 v[6:7], v[6:7], v[8:9]
	s_nop 0
	v_cvt_pk_bf16_f32 v3, v6, v7
	global_store_dwordx4 v[4:5], v[0:3], off
	s_barrier
	s_cbranch_scc1 .LBB0_725
